# S5 pass 2: next chunk's input-projection MFMAs issued inside the current chunk's recurrence steps
# speedup vs baseline: 1.0077x; 1.0004x over previous
.LBB0_873:
	v_mov_b32_e32 v224, 0x3d122279
	v_mov_b32_e32 v225, 0x3d122279
	v_mov_b32_e32 v226, 0x3f4c422a
	v_mov_b32_e32 v227, 0x3f4c422a
	v_mov_b32_e32 v228, 0xc038aa3b
	v_mov_b32_e32 v229, 0xc038aa3b
	v_mov_b32_e32 v230, 1.0
	v_mov_b32_e32 v231, 1.0
	v_cndmask_b32_e64 v93, v83, 0, s[10:11]
	v_cndmask_b32_e64 v92, v82, 0, s[10:11]
	v_cndmask_b32_e64 v91, v81, 0, s[10:11]
	v_cndmask_b32_e64 v90, v80, 0, s[10:11]
	v_add_u32_e32 v81, v139, v141
	v_add_u32_e32 v83, v139, v142
	v_mfma_f32_16x16x32_bf16 v[192:195], v[90:93], v[0:3], 0
	v_add_u32_e32 v88, v139, v143
	v_add_u32_e32 v82, s86, v140
	v_mov_b32_e32 v240, v86
	v_mov_b32_e32 v241, v87
	v_mfma_f32_16x16x32_bf16 v[196:199], v[90:93], v[4:7], 0
	v_mfma_f32_16x16x32_bf16 v[200:203], v[90:93], v[8:11], 0
	s_nop 2
	s_nop 2
	v_cndmask_b32_e64 v79, v79, 0, s[10:11]
	v_mfma_f32_16x16x32_bf16 v[204:207], v[90:93], v[12:15], 0
	v_cndmask_b32_e64 v78, v78, 0, s[10:11]
	v_cndmask_b32_e64 v77, v77, 0, s[10:11]
	v_cndmask_b32_e64 v76, v76, 0, s[10:11]
	v_mfma_f32_16x16x32_bf16 v[212:215], v[90:93], v[20:23], 0
	v_cndmask_b32_e64 v75, v75, 0, s[10:11]
	v_cndmask_b32_e64 v74, v74, 0, s[10:11]
	v_cndmask_b32_e64 v73, v73, 0, s[10:11]
	v_mfma_f32_16x16x32_bf16 v[208:211], v[90:93], v[16:19], 0
	s_nop 6
	v_mfma_f32_16x16x32_bf16 v[216:219], v[90:93], v[24:27], 0
	s_nop 6
	v_mfma_f32_16x16x32_bf16 v[220:223], v[90:93], v[28:31], 0
	v_cndmask_b32_e64 v72, v72, 0, s[10:11]
	v_cndmask_b32_e64 v71, v71, 0, s[10:11]
	v_cndmask_b32_e64 v70, v70, 0, s[10:11]
	v_mfma_f32_16x16x32_bf16 v[90:93], v[90:93], v[48:51], 0
	v_cndmask_b32_e64 v69, v69, 0, s[10:11]
	s_nop 2
	s_nop 7
	v_permlane16_swap_b32_e32 v192, v196
	v_permlane16_swap_b32_e32 v193, v197
	v_permlane16_swap_b32_e32 v194, v198
	v_permlane16_swap_b32_e32 v195, v199
	v_permlane16_swap_b32_e32 v200, v204
	v_permlane16_swap_b32_e32 v201, v205
	v_permlane16_swap_b32_e32 v202, v206
	v_permlane16_swap_b32_e32 v203, v207
	v_permlane16_swap_b32_e32 v208, v212
	v_permlane16_swap_b32_e32 v209, v213
	v_permlane16_swap_b32_e32 v210, v214
	v_permlane16_swap_b32_e32 v211, v215
	v_permlane16_swap_b32_e32 v216, v220
	v_permlane16_swap_b32_e32 v217, v221
	v_permlane16_swap_b32_e32 v218, v222
	v_permlane16_swap_b32_e32 v219, v223
	v_permlane32_swap_b32_e32 v192, v200
	v_permlane32_swap_b32_e32 v193, v201
	v_permlane32_swap_b32_e32 v194, v202
	v_permlane32_swap_b32_e32 v195, v203
	v_permlane32_swap_b32_e32 v196, v204
	v_permlane32_swap_b32_e32 v197, v205
	v_permlane32_swap_b32_e32 v198, v206
	v_permlane32_swap_b32_e32 v199, v207
	v_permlane32_swap_b32_e32 v208, v216
	v_permlane32_swap_b32_e32 v209, v217
	v_permlane32_swap_b32_e32 v210, v218
	v_permlane32_swap_b32_e32 v211, v219
	v_permlane32_swap_b32_e32 v212, v220
	v_permlane32_swap_b32_e32 v213, v221
	v_permlane32_swap_b32_e32 v214, v222
	v_permlane32_swap_b32_e32 v215, v223
	v_fma_f32 v242, -v132, v241, v192
	v_fma_f32 v243, v132, v240, v208
	v_fma_f32 v244, v128, v240, v242
	v_fma_f32 v245, v128, v241, v243
	v_cvt_pk_bf16_f32 v248, v244, v245
	ds_write_b32 v149, v248 offset:10240
	v_fma_f32 v242, -v132, v245, v193
	v_fma_f32 v243, v132, v244, v209
	v_fma_f32 v246, v128, v244, v242
	v_fma_f32 v247, v128, v245, v243
	v_cvt_pk_bf16_f32 v249, v246, v247
	ds_write_b32 v149, v249 offset:10512
	v_fma_f32 v242, -v132, v247, v194
	v_fma_f32 v243, v132, v246, v210
	v_fma_f32 v244, v128, v246, v242
	v_fma_f32 v245, v128, v247, v243
	v_cvt_pk_bf16_f32 v248, v244, v245
	ds_write_b32 v149, v248 offset:10784
	v_fma_f32 v242, -v132, v245, v195
	v_fma_f32 v243, v132, v244, v211
	v_fma_f32 v246, v128, v244, v242
	v_fma_f32 v247, v128, v245, v243
	v_cvt_pk_bf16_f32 v249, v246, v247
	ds_write_b32 v149, v249 offset:11056
	v_mfma_f32_16x16x32_bf16 v[192:195], v[76:79], v[0:3], 0
	v_mfma_f32_16x16x32_bf16 v[208:211], v[76:79], v[16:19], 0
	v_fma_f32 v242, -v132, v247, v196
	v_fma_f32 v243, v132, v246, v212
	v_fma_f32 v244, v128, v246, v242
	v_fma_f32 v245, v128, v247, v243
	v_cvt_pk_bf16_f32 v248, v244, v245
	ds_write_b32 v149, v248 offset:11328
	v_fma_f32 v242, -v132, v245, v197
	v_fma_f32 v243, v132, v244, v213
	v_fma_f32 v246, v128, v244, v242
	v_fma_f32 v247, v128, v245, v243
	v_cvt_pk_bf16_f32 v249, v246, v247
	ds_write_b32 v149, v249 offset:11600
	v_fma_f32 v242, -v132, v247, v198
	v_fma_f32 v243, v132, v246, v214
	v_fma_f32 v244, v128, v246, v242
	v_fma_f32 v245, v128, v247, v243
	v_cvt_pk_bf16_f32 v248, v244, v245
	ds_write_b32 v149, v248 offset:11872
	v_fma_f32 v242, -v132, v245, v199
	v_fma_f32 v243, v132, v244, v215
	v_fma_f32 v246, v128, v244, v242
	v_fma_f32 v247, v128, v245, v243
	v_cvt_pk_bf16_f32 v249, v246, v247
	ds_write_b32 v149, v249 offset:12144
	v_mfma_f32_16x16x32_bf16 v[196:199], v[76:79], v[4:7], 0
	v_mfma_f32_16x16x32_bf16 v[212:215], v[76:79], v[20:23], 0
	v_fma_f32 v242, -v132, v247, v200
	v_fma_f32 v243, v132, v246, v216
	v_fma_f32 v244, v128, v246, v242
	v_fma_f32 v245, v128, v247, v243
	v_cvt_pk_bf16_f32 v248, v244, v245
	ds_write_b32 v149, v248 offset:12416
	v_fma_f32 v242, -v132, v245, v201
	v_fma_f32 v243, v132, v244, v217
	v_fma_f32 v246, v128, v244, v242
	v_fma_f32 v247, v128, v245, v243
	v_cvt_pk_bf16_f32 v249, v246, v247
	ds_write_b32 v149, v249 offset:12688
	v_fma_f32 v242, -v132, v247, v202
	v_fma_f32 v243, v132, v246, v218
	v_fma_f32 v244, v128, v246, v242
	v_fma_f32 v245, v128, v247, v243
	v_cvt_pk_bf16_f32 v248, v244, v245
	ds_write_b32 v149, v248 offset:12960
	v_fma_f32 v242, -v132, v245, v203
	v_fma_f32 v243, v132, v244, v219
	v_fma_f32 v246, v128, v244, v242
	v_fma_f32 v247, v128, v245, v243
	v_cvt_pk_bf16_f32 v249, v246, v247
	ds_write_b32 v149, v249 offset:13232
	v_mfma_f32_16x16x32_bf16 v[200:203], v[76:79], v[8:11], 0
	v_mfma_f32_16x16x32_bf16 v[216:219], v[76:79], v[24:27], 0
	v_fma_f32 v242, -v132, v247, v204
	v_fma_f32 v243, v132, v246, v220
	v_fma_f32 v244, v128, v246, v242
	v_fma_f32 v245, v128, v247, v243
	v_cvt_pk_bf16_f32 v248, v244, v245
	ds_write_b32 v149, v248 offset:13504
	v_fma_f32 v242, -v132, v245, v205
	v_fma_f32 v243, v132, v244, v221
	v_fma_f32 v246, v128, v244, v242
	v_fma_f32 v247, v128, v245, v243
	v_cvt_pk_bf16_f32 v249, v246, v247
	ds_write_b32 v149, v249 offset:13776
	v_fma_f32 v242, -v132, v247, v206
	v_fma_f32 v243, v132, v246, v222
	v_fma_f32 v244, v128, v246, v242
	v_fma_f32 v245, v128, v247, v243
	v_cvt_pk_bf16_f32 v248, v244, v245
	ds_write_b32 v149, v248 offset:14048
	v_fma_f32 v242, -v132, v245, v207
	v_fma_f32 v243, v132, v244, v223
	v_fma_f32 v87, v128, v244, v242
	v_fma_f32 v86, v128, v245, v243
	v_cvt_pk_bf16_f32 v249, v87, v86
	ds_write_b32 v149, v249 offset:14320
	v_mfma_f32_16x16x32_bf16 v[204:207], v[76:79], v[12:15], 0
	v_mfma_f32_16x16x32_bf16 v[220:223], v[76:79], v[28:31], 0
	s_waitcnt lgkmcnt(0)
	v_add_u32_e32 v80, v150, v138
	ds_read_b128 v[94:97], v80 offset:10240
	ds_read_b128 v[98:101], v80 offset:10304
	ds_read_b128 v[184:187], v80 offset:10368
	ds_read_b128 v[188:191], v80 offset:10432
	v_cndmask_b32_e64 v68, v68, 0, s[10:11]
	s_add_u32 s30, s30, 0x40000
	s_addc_u32 s31, s31, 0
	s_cmp_eq_u32 s30, 0x240000
	s_cselect_b64 s[34:35], -1, 0
	s_nop 5
	s_nop 0
	s_nop 3
	v_mov_b32_e32 v240, v87
	v_mov_b32_e32 v241, v86
	s_nop 0
	s_nop 4
	v_mfma_f32_16x16x32_bf16 v[76:79], v[76:79], v[48:51], 0
	s_nop 5
	s_nop 7
	v_permlane16_swap_b32_e32 v192, v196
	v_permlane16_swap_b32_e32 v193, v197
	v_permlane16_swap_b32_e32 v194, v198
	v_permlane16_swap_b32_e32 v195, v199
	v_permlane16_swap_b32_e32 v200, v204
	v_permlane16_swap_b32_e32 v201, v205
	v_permlane16_swap_b32_e32 v202, v206
	v_permlane16_swap_b32_e32 v203, v207
	v_permlane16_swap_b32_e32 v208, v212
	v_permlane16_swap_b32_e32 v209, v213
	v_permlane16_swap_b32_e32 v210, v214
	v_permlane16_swap_b32_e32 v211, v215
	v_permlane16_swap_b32_e32 v216, v220
	v_permlane16_swap_b32_e32 v217, v221
	v_permlane16_swap_b32_e32 v218, v222
	v_permlane16_swap_b32_e32 v219, v223
	v_permlane32_swap_b32_e32 v192, v200
	v_permlane32_swap_b32_e32 v193, v201
	v_permlane32_swap_b32_e32 v194, v202
	v_permlane32_swap_b32_e32 v195, v203
	v_permlane32_swap_b32_e32 v196, v204
	v_permlane32_swap_b32_e32 v197, v205
	v_permlane32_swap_b32_e32 v198, v206
	v_permlane32_swap_b32_e32 v199, v207
	v_permlane32_swap_b32_e32 v208, v216
	v_permlane32_swap_b32_e32 v209, v217
	v_permlane32_swap_b32_e32 v210, v218
	v_permlane32_swap_b32_e32 v211, v219
	v_permlane32_swap_b32_e32 v212, v220
	v_permlane32_swap_b32_e32 v213, v221
	v_permlane32_swap_b32_e32 v214, v222
	v_permlane32_swap_b32_e32 v215, v223
	v_fma_f32 v242, -v132, v241, v192
	v_fma_f32 v243, v132, v240, v208
	v_fma_f32 v244, v128, v240, v242
	v_fma_f32 v245, v128, v241, v243
	v_cvt_pk_bf16_f32 v248, v244, v245
	ds_write_b32 v149, v248 offset:10240
	s_waitcnt lgkmcnt(4)
	v_mfma_f32_16x16x32_bf16 v[90:93], v[94:97], v[32:35], v[90:93]
	v_fma_f32 v242, -v132, v245, v193
	v_fma_f32 v243, v132, v244, v209
	v_fma_f32 v246, v128, v244, v242
	v_fma_f32 v247, v128, v245, v243
	v_cvt_pk_bf16_f32 v249, v246, v247
	ds_write_b32 v149, v249 offset:10512
	s_waitcnt lgkmcnt(4)
	v_mfma_f32_16x16x32_bf16 v[90:93], v[98:101], v[36:39], v[90:93]
	v_fma_f32 v242, -v132, v247, v194
	v_fma_f32 v243, v132, v246, v210
	v_fma_f32 v244, v128, v246, v242
	v_fma_f32 v245, v128, v247, v243
	v_cvt_pk_bf16_f32 v248, v244, v245
	ds_write_b32 v149, v248 offset:10784
	s_waitcnt lgkmcnt(4)
	v_mfma_f32_16x16x32_bf16 v[90:93], v[184:187], v[40:43], v[90:93]
	v_fma_f32 v242, -v132, v245, v195
	v_fma_f32 v243, v132, v244, v211
	v_fma_f32 v246, v128, v244, v242
	v_fma_f32 v247, v128, v245, v243
	v_cvt_pk_bf16_f32 v249, v246, v247
	ds_write_b32 v149, v249 offset:11056
	v_mfma_f32_16x16x32_bf16 v[192:195], v[72:75], v[0:3], 0
	v_mfma_f32_16x16x32_bf16 v[208:211], v[72:75], v[16:19], 0
	s_waitcnt lgkmcnt(4)
	v_mfma_f32_16x16x32_bf16 v[90:93], v[188:191], v[44:47], v[90:93]
	v_fma_f32 v242, -v132, v247, v196
	v_fma_f32 v243, v132, v246, v212
	v_fma_f32 v244, v128, v246, v242
	v_fma_f32 v245, v128, v247, v243
	v_cvt_pk_bf16_f32 v248, v244, v245
	ds_write_b32 v149, v248 offset:11328
	v_fma_f32 v242, -v132, v245, v197
	v_fma_f32 v243, v132, v244, v213
	v_fma_f32 v246, v128, v244, v242
	v_fma_f32 v247, v128, v245, v243
	v_cvt_pk_bf16_f32 v249, v246, v247
	ds_write_b32 v149, v249 offset:11600
	v_fma_f32 v242, -v132, v247, v198
	v_fma_f32 v243, v132, v246, v214
	v_fma_f32 v244, v128, v246, v242
	v_fma_f32 v245, v128, v247, v243
	v_cvt_pk_bf16_f32 v248, v244, v245
	ds_write_b32 v149, v248 offset:11872
	v_pk_mul_f32 v[232:233], v[90:91], v[224:225]
	v_pk_mul_f32 v[234:235], v[92:93], v[224:225]
	v_pk_fma_f32 v[232:233], v[90:91], v[232:233], v[226:227]
	v_fma_f32 v242, -v132, v245, v199
	v_fma_f32 v243, v132, v244, v215
	v_fma_f32 v246, v128, v244, v242
	v_fma_f32 v247, v128, v245, v243
	v_cvt_pk_bf16_f32 v249, v246, v247
	ds_write_b32 v149, v249 offset:12144
	v_mfma_f32_16x16x32_bf16 v[196:199], v[72:75], v[4:7], 0
	v_mfma_f32_16x16x32_bf16 v[212:215], v[72:75], v[20:23], 0
	v_pk_fma_f32 v[234:235], v[92:93], v[234:235], v[226:227]
	v_pk_mul_f32 v[232:233], v[90:91], v[232:233]
	v_pk_mul_f32 v[234:235], v[92:93], v[234:235]
	v_fma_f32 v242, -v132, v247, v200
	v_fma_f32 v243, v132, v246, v216
	v_fma_f32 v244, v128, v246, v242
	v_fma_f32 v245, v128, v247, v243
	v_cvt_pk_bf16_f32 v248, v244, v245
	ds_write_b32 v149, v248 offset:12416
	v_pk_mul_f32 v[232:233], v[232:233], v[228:229]
	v_pk_mul_f32 v[234:235], v[234:235], v[228:229]
	v_exp_f32_e32 v232, v232
	v_fma_f32 v242, -v132, v245, v201
	v_fma_f32 v243, v132, v244, v217
	v_fma_f32 v246, v128, v244, v242
	v_fma_f32 v247, v128, v245, v243
	v_cvt_pk_bf16_f32 v249, v246, v247
	ds_write_b32 v149, v249 offset:12688
	v_exp_f32_e32 v233, v233
	v_exp_f32_e32 v234, v234
	v_exp_f32_e32 v235, v235
	v_fma_f32 v242, -v132, v247, v202
	v_fma_f32 v243, v132, v246, v218
	v_fma_f32 v244, v128, v246, v242
	v_fma_f32 v245, v128, v247, v243
	v_cvt_pk_bf16_f32 v248, v244, v245
	ds_write_b32 v149, v248 offset:12960
	v_pk_add_f32 v[232:233], v[232:233], v[230:231]
	v_pk_add_f32 v[234:235], v[234:235], v[230:231]
	v_rcp_f32_e32 v232, v232
	v_fma_f32 v242, -v132, v245, v203
	v_fma_f32 v243, v132, v244, v219
	v_fma_f32 v246, v128, v244, v242
	v_fma_f32 v247, v128, v245, v243
	v_cvt_pk_bf16_f32 v249, v246, v247
	ds_write_b32 v149, v249 offset:13232
	v_mfma_f32_16x16x32_bf16 v[200:203], v[72:75], v[8:11], 0
	v_mfma_f32_16x16x32_bf16 v[216:219], v[72:75], v[24:27], 0
	v_rcp_f32_e32 v233, v233
	v_rcp_f32_e32 v234, v234
	v_rcp_f32_e32 v235, v235
	v_fma_f32 v242, -v132, v247, v204
	v_fma_f32 v243, v132, v246, v220
	v_fma_f32 v244, v128, v246, v242
	v_fma_f32 v245, v128, v247, v243
	v_cvt_pk_bf16_f32 v248, v244, v245
	ds_write_b32 v149, v248 offset:13504
	v_pk_mul_f32 v[232:233], v[90:91], v[232:233]
	v_pk_mul_f32 v[234:235], v[92:93], v[234:235]
	v_cvt_pk_bf16_f32 v236, v232, v232
	v_fma_f32 v242, -v132, v245, v205
	v_fma_f32 v243, v132, v244, v221
	v_fma_f32 v246, v128, v244, v242
	v_fma_f32 v247, v128, v245, v243
	v_cvt_pk_bf16_f32 v249, v246, v247
	ds_write_b32 v149, v249 offset:13776
	v_cvt_pk_bf16_f32 v237, v233, v233
	v_cvt_pk_bf16_f32 v238, v234, v234
	v_cvt_pk_bf16_f32 v239, v235, v235
	v_fma_f32 v242, -v132, v247, v206
	v_fma_f32 v243, v132, v246, v222
	v_fma_f32 v244, v128, v246, v242
	v_fma_f32 v245, v128, v247, v243
	v_cvt_pk_bf16_f32 v248, v244, v245
	ds_write_b32 v149, v248 offset:14048
	ds_write_b16 v160, v236 offset:14592
	ds_write_b16 v160, v237 offset:14624
	ds_write_b16 v160, v238 offset:14656
	v_fma_f32 v242, -v132, v245, v207
	v_fma_f32 v243, v132, v244, v223
	v_fma_f32 v87, v128, v244, v242
	v_fma_f32 v86, v128, v245, v243
	v_cvt_pk_bf16_f32 v249, v87, v86
	ds_write_b32 v149, v249 offset:14320
	v_mfma_f32_16x16x32_bf16 v[204:207], v[72:75], v[12:15], 0
	v_mfma_f32_16x16x32_bf16 v[220:223], v[72:75], v[28:31], 0
	ds_write_b16 v161, v239 offset:14592
	s_waitcnt lgkmcnt(0)
	ds_read_b128 v[90:93], v80 offset:10240
	ds_read_b128 v[94:97], v80 offset:10304
	ds_read_b128 v[184:187], v80 offset:10368
	ds_read_b128 v[188:191], v80 offset:10432
	s_nop 5
	s_nop 0
	s_nop 3
	v_mov_b32_e32 v240, v87
	v_mov_b32_e32 v241, v86
	s_nop 0
	s_nop 4
	v_mfma_f32_16x16x32_bf16 v[72:75], v[72:75], v[48:51], 0
	s_nop 5
	s_nop 7
	v_permlane16_swap_b32_e32 v192, v196
	v_permlane16_swap_b32_e32 v193, v197
	v_permlane16_swap_b32_e32 v194, v198
	v_permlane16_swap_b32_e32 v195, v199
	v_permlane16_swap_b32_e32 v200, v204
	v_permlane16_swap_b32_e32 v201, v205
	v_permlane16_swap_b32_e32 v202, v206
	v_permlane16_swap_b32_e32 v203, v207
	v_permlane16_swap_b32_e32 v208, v212
	v_permlane16_swap_b32_e32 v209, v213
	v_permlane16_swap_b32_e32 v210, v214
	v_permlane16_swap_b32_e32 v211, v215
	v_permlane16_swap_b32_e32 v216, v220
	v_permlane16_swap_b32_e32 v217, v221
	v_permlane16_swap_b32_e32 v218, v222
	v_permlane16_swap_b32_e32 v219, v223
	v_permlane32_swap_b32_e32 v192, v200
	v_permlane32_swap_b32_e32 v193, v201
	v_permlane32_swap_b32_e32 v194, v202
	v_permlane32_swap_b32_e32 v195, v203
	v_permlane32_swap_b32_e32 v196, v204
	v_permlane32_swap_b32_e32 v197, v205
	v_permlane32_swap_b32_e32 v198, v206
	v_permlane32_swap_b32_e32 v199, v207
	v_permlane32_swap_b32_e32 v208, v216
	v_permlane32_swap_b32_e32 v209, v217
	v_permlane32_swap_b32_e32 v210, v218
	v_permlane32_swap_b32_e32 v211, v219
	v_permlane32_swap_b32_e32 v212, v220
	v_permlane32_swap_b32_e32 v213, v221
	v_permlane32_swap_b32_e32 v214, v222
	v_permlane32_swap_b32_e32 v215, v223
	v_fma_f32 v242, -v132, v241, v192
	v_fma_f32 v243, v132, v240, v208
	v_fma_f32 v244, v128, v240, v242
	v_fma_f32 v245, v128, v241, v243
	v_cvt_pk_bf16_f32 v248, v244, v245
	ds_write_b32 v149, v248 offset:10240
	s_waitcnt lgkmcnt(4)
	v_mfma_f32_16x16x32_bf16 v[76:79], v[90:93], v[32:35], v[76:79]
	v_fma_f32 v242, -v132, v245, v193
	v_fma_f32 v243, v132, v244, v209
	v_fma_f32 v246, v128, v244, v242
	v_fma_f32 v247, v128, v245, v243
	v_cvt_pk_bf16_f32 v249, v246, v247
	ds_write_b32 v149, v249 offset:10512
	s_waitcnt lgkmcnt(4)
	v_mfma_f32_16x16x32_bf16 v[76:79], v[94:97], v[36:39], v[76:79]
	v_fma_f32 v242, -v132, v247, v194
	v_fma_f32 v243, v132, v246, v210
	v_fma_f32 v244, v128, v246, v242
	v_fma_f32 v245, v128, v247, v243
	v_cvt_pk_bf16_f32 v248, v244, v245
	ds_write_b32 v149, v248 offset:10784
	s_waitcnt lgkmcnt(4)
	v_mfma_f32_16x16x32_bf16 v[76:79], v[184:187], v[40:43], v[76:79]
	v_fma_f32 v242, -v132, v245, v195
	v_fma_f32 v243, v132, v244, v211
	v_fma_f32 v246, v128, v244, v242
	v_fma_f32 v247, v128, v245, v243
	v_cvt_pk_bf16_f32 v249, v246, v247
	ds_write_b32 v149, v249 offset:11056
	v_mfma_f32_16x16x32_bf16 v[192:195], v[68:71], v[0:3], 0
	v_mfma_f32_16x16x32_bf16 v[208:211], v[68:71], v[16:19], 0
	s_waitcnt lgkmcnt(4)
	v_mfma_f32_16x16x32_bf16 v[76:79], v[188:191], v[44:47], v[76:79]
	v_fma_f32 v242, -v132, v247, v196
	v_fma_f32 v243, v132, v246, v212
	v_fma_f32 v244, v128, v246, v242
	v_fma_f32 v245, v128, v247, v243
	v_cvt_pk_bf16_f32 v248, v244, v245
	ds_write_b32 v149, v248 offset:11328
	v_fma_f32 v242, -v132, v245, v197
	v_fma_f32 v243, v132, v244, v213
	v_fma_f32 v246, v128, v244, v242
	v_fma_f32 v247, v128, v245, v243
	v_cvt_pk_bf16_f32 v249, v246, v247
	ds_write_b32 v149, v249 offset:11600
	v_fma_f32 v242, -v132, v247, v198
	v_fma_f32 v243, v132, v246, v214
	v_fma_f32 v244, v128, v246, v242
	v_fma_f32 v245, v128, v247, v243
	v_cvt_pk_bf16_f32 v248, v244, v245
	ds_write_b32 v149, v248 offset:11872
	v_pk_mul_f32 v[232:233], v[76:77], v[224:225]
	v_pk_mul_f32 v[234:235], v[78:79], v[224:225]
	v_pk_fma_f32 v[232:233], v[76:77], v[232:233], v[226:227]
	v_fma_f32 v242, -v132, v245, v199
	v_fma_f32 v243, v132, v244, v215
	v_fma_f32 v246, v128, v244, v242
	v_fma_f32 v247, v128, v245, v243
	v_cvt_pk_bf16_f32 v249, v246, v247
	ds_write_b32 v149, v249 offset:12144
	v_mfma_f32_16x16x32_bf16 v[196:199], v[68:71], v[4:7], 0
	v_mfma_f32_16x16x32_bf16 v[212:215], v[68:71], v[20:23], 0
	v_pk_fma_f32 v[234:235], v[78:79], v[234:235], v[226:227]
	v_pk_mul_f32 v[232:233], v[76:77], v[232:233]
	v_pk_mul_f32 v[234:235], v[78:79], v[234:235]
	v_fma_f32 v242, -v132, v247, v200
	v_fma_f32 v243, v132, v246, v216
	v_fma_f32 v244, v128, v246, v242
	v_fma_f32 v245, v128, v247, v243
	v_cvt_pk_bf16_f32 v248, v244, v245
	ds_write_b32 v149, v248 offset:12416
	v_pk_mul_f32 v[232:233], v[232:233], v[228:229]
	v_pk_mul_f32 v[234:235], v[234:235], v[228:229]
	v_exp_f32_e32 v232, v232
	v_fma_f32 v242, -v132, v245, v201
	v_fma_f32 v243, v132, v244, v217
	v_fma_f32 v246, v128, v244, v242
	v_fma_f32 v247, v128, v245, v243
	v_cvt_pk_bf16_f32 v249, v246, v247
	ds_write_b32 v149, v249 offset:12688
	v_exp_f32_e32 v233, v233
	v_exp_f32_e32 v234, v234
	v_exp_f32_e32 v235, v235
	v_fma_f32 v242, -v132, v247, v202
	v_fma_f32 v243, v132, v246, v218
	v_fma_f32 v244, v128, v246, v242
	v_fma_f32 v245, v128, v247, v243
	v_cvt_pk_bf16_f32 v248, v244, v245
	ds_write_b32 v149, v248 offset:12960
	v_pk_add_f32 v[232:233], v[232:233], v[230:231]
	v_pk_add_f32 v[234:235], v[234:235], v[230:231]
	v_rcp_f32_e32 v232, v232
	v_fma_f32 v242, -v132, v245, v203
	v_fma_f32 v243, v132, v244, v219
	v_fma_f32 v246, v128, v244, v242
	v_fma_f32 v247, v128, v245, v243
	v_cvt_pk_bf16_f32 v249, v246, v247
	ds_write_b32 v149, v249 offset:13232
	v_mfma_f32_16x16x32_bf16 v[200:203], v[68:71], v[8:11], 0
	v_mfma_f32_16x16x32_bf16 v[216:219], v[68:71], v[24:27], 0
	v_rcp_f32_e32 v233, v233
	v_rcp_f32_e32 v234, v234
	v_rcp_f32_e32 v235, v235
	v_fma_f32 v242, -v132, v247, v204
	v_fma_f32 v243, v132, v246, v220
	v_fma_f32 v244, v128, v246, v242
	v_fma_f32 v245, v128, v247, v243
	v_cvt_pk_bf16_f32 v248, v244, v245
	ds_write_b32 v149, v248 offset:13504
	v_pk_mul_f32 v[232:233], v[76:77], v[232:233]
	v_pk_mul_f32 v[234:235], v[78:79], v[234:235]
	v_cvt_pk_bf16_f32 v236, v232, v232
	v_fma_f32 v242, -v132, v245, v205
	v_fma_f32 v243, v132, v244, v221
	v_fma_f32 v246, v128, v244, v242
	v_fma_f32 v247, v128, v245, v243
	v_cvt_pk_bf16_f32 v249, v246, v247
	ds_write_b32 v149, v249 offset:13776
	v_cvt_pk_bf16_f32 v237, v233, v233
	v_cvt_pk_bf16_f32 v238, v234, v234
	v_cvt_pk_bf16_f32 v239, v235, v235
	v_fma_f32 v242, -v132, v247, v206
	v_fma_f32 v243, v132, v246, v222
	v_fma_f32 v244, v128, v246, v242
	v_fma_f32 v245, v128, v247, v243
	v_cvt_pk_bf16_f32 v248, v244, v245
	ds_write_b32 v149, v248 offset:14048
	ds_write_b16 v160, v236 offset:15104
	ds_write_b16 v160, v237 offset:15136
	ds_write_b16 v160, v238 offset:15168
	v_fma_f32 v242, -v132, v245, v207
	v_fma_f32 v243, v132, v244, v223
	v_fma_f32 v110, v128, v244, v242
	v_fma_f32 v111, v128, v245, v243
	v_cvt_pk_bf16_f32 v249, v110, v111
	ds_write_b32 v149, v249 offset:14320
	v_mfma_f32_16x16x32_bf16 v[204:207], v[68:71], v[12:15], 0
	v_mfma_f32_16x16x32_bf16 v[220:223], v[68:71], v[28:31], 0
	ds_write_b16 v162, v239 offset:14592
	s_waitcnt lgkmcnt(0)
	ds_read_b128 v[76:79], v80 offset:10240
	ds_read_b128 v[90:93], v80 offset:10304
	ds_read_b128 v[184:187], v80 offset:10368
	ds_read_b128 v[188:191], v80 offset:10432
	s_nop 5
	s_nop 0
	s_nop 3
	s_nop 2
	s_nop 2
	v_mov_b32_e32 v240, v110
	v_mov_b32_e32 v241, v111
	v_mfma_f32_16x16x32_bf16 v[68:71], v[68:71], v[48:51], 0
	s_nop 5
	s_nop 7
	v_permlane16_swap_b32_e32 v192, v196
	v_permlane16_swap_b32_e32 v193, v197
	v_permlane16_swap_b32_e32 v194, v198
	v_permlane16_swap_b32_e32 v195, v199
	v_permlane16_swap_b32_e32 v200, v204
	v_permlane16_swap_b32_e32 v201, v205
	v_permlane16_swap_b32_e32 v202, v206
	v_permlane16_swap_b32_e32 v203, v207
	v_permlane16_swap_b32_e32 v208, v212
	v_permlane16_swap_b32_e32 v209, v213
	v_permlane16_swap_b32_e32 v210, v214
	v_permlane16_swap_b32_e32 v211, v215
	v_permlane16_swap_b32_e32 v216, v220
	v_permlane16_swap_b32_e32 v217, v221
	v_permlane16_swap_b32_e32 v218, v222
	v_permlane16_swap_b32_e32 v219, v223
	v_permlane32_swap_b32_e32 v192, v200
	v_permlane32_swap_b32_e32 v193, v201
	v_permlane32_swap_b32_e32 v194, v202
	v_permlane32_swap_b32_e32 v195, v203
	v_permlane32_swap_b32_e32 v196, v204
	v_permlane32_swap_b32_e32 v197, v205
	v_permlane32_swap_b32_e32 v198, v206
	v_permlane32_swap_b32_e32 v199, v207
	v_permlane32_swap_b32_e32 v208, v216
	v_permlane32_swap_b32_e32 v209, v217
	v_permlane32_swap_b32_e32 v210, v218
	v_permlane32_swap_b32_e32 v211, v219
	v_permlane32_swap_b32_e32 v212, v220
	v_permlane32_swap_b32_e32 v213, v221
	v_permlane32_swap_b32_e32 v214, v222
	v_permlane32_swap_b32_e32 v215, v223
	v_fma_f32 v242, -v132, v241, v192
	v_fma_f32 v243, v132, v240, v208
	v_fma_f32 v244, v128, v240, v242
	v_fma_f32 v245, v128, v241, v243
	v_cvt_pk_bf16_f32 v248, v244, v245
	ds_write_b32 v149, v248 offset:10240
	s_waitcnt lgkmcnt(4)
	v_mfma_f32_16x16x32_bf16 v[72:75], v[76:79], v[32:35], v[72:75]
	v_fma_f32 v242, -v132, v245, v193
	v_fma_f32 v243, v132, v244, v209
	v_fma_f32 v246, v128, v244, v242
	v_fma_f32 v247, v128, v245, v243
	v_cvt_pk_bf16_f32 v249, v246, v247
	ds_write_b32 v149, v249 offset:10512
	s_waitcnt lgkmcnt(4)
	v_mfma_f32_16x16x32_bf16 v[72:75], v[90:93], v[36:39], v[72:75]
	v_fma_f32 v242, -v132, v247, v194
	v_fma_f32 v243, v132, v246, v210
	v_fma_f32 v244, v128, v246, v242
	v_fma_f32 v245, v128, v247, v243
	v_cvt_pk_bf16_f32 v248, v244, v245
	ds_write_b32 v149, v248 offset:10784
	s_waitcnt lgkmcnt(4)
	v_mfma_f32_16x16x32_bf16 v[72:75], v[184:187], v[40:43], v[72:75]
	v_fma_f32 v242, -v132, v245, v195
	v_fma_f32 v243, v132, v244, v211
	v_fma_f32 v246, v128, v244, v242
	v_fma_f32 v247, v128, v245, v243
	v_cvt_pk_bf16_f32 v249, v246, v247
	ds_write_b32 v149, v249 offset:11056
	s_waitcnt lgkmcnt(4)
	v_mfma_f32_16x16x32_bf16 v[72:75], v[188:191], v[44:47], v[72:75]
	v_fma_f32 v242, -v132, v247, v196
	v_fma_f32 v243, v132, v246, v212
	v_fma_f32 v244, v128, v246, v242
	v_fma_f32 v245, v128, v247, v243
	v_cvt_pk_bf16_f32 v248, v244, v245
	ds_write_b32 v149, v248 offset:11328
	v_fma_f32 v242, -v132, v245, v197
	v_fma_f32 v243, v132, v244, v213
	v_fma_f32 v246, v128, v244, v242
	v_fma_f32 v247, v128, v245, v243
	v_cvt_pk_bf16_f32 v249, v246, v247
	ds_write_b32 v149, v249 offset:11600
	v_fma_f32 v242, -v132, v247, v198
	v_fma_f32 v243, v132, v246, v214
	v_fma_f32 v244, v128, v246, v242
	v_fma_f32 v245, v128, v247, v243
	v_cvt_pk_bf16_f32 v248, v244, v245
	ds_write_b32 v149, v248 offset:11872
	v_pk_mul_f32 v[232:233], v[72:73], v[224:225]
	v_pk_mul_f32 v[234:235], v[74:75], v[224:225]
	v_pk_fma_f32 v[232:233], v[72:73], v[232:233], v[226:227]
	v_fma_f32 v242, -v132, v245, v199
	v_fma_f32 v243, v132, v244, v215
	v_fma_f32 v246, v128, v244, v242
	v_fma_f32 v247, v128, v245, v243
	v_cvt_pk_bf16_f32 v249, v246, v247
	ds_write_b32 v149, v249 offset:12144
	v_pk_fma_f32 v[234:235], v[74:75], v[234:235], v[226:227]
	v_pk_mul_f32 v[232:233], v[72:73], v[232:233]
	v_pk_mul_f32 v[234:235], v[74:75], v[234:235]
	v_fma_f32 v242, -v132, v247, v200
	v_fma_f32 v243, v132, v246, v216
	v_fma_f32 v244, v128, v246, v242
	v_fma_f32 v245, v128, v247, v243
	v_cvt_pk_bf16_f32 v248, v244, v245
	ds_write_b32 v149, v248 offset:12416
	v_pk_mul_f32 v[232:233], v[232:233], v[228:229]
	v_pk_mul_f32 v[234:235], v[234:235], v[228:229]
	v_exp_f32_e32 v232, v232
	v_fma_f32 v242, -v132, v245, v201
	v_fma_f32 v243, v132, v244, v217
	v_fma_f32 v246, v128, v244, v242
	v_fma_f32 v247, v128, v245, v243
	v_cvt_pk_bf16_f32 v249, v246, v247
	ds_write_b32 v149, v249 offset:12688
	v_exp_f32_e32 v233, v233
	v_exp_f32_e32 v234, v234
	v_exp_f32_e32 v235, v235
	v_fma_f32 v242, -v132, v247, v202
	v_fma_f32 v243, v132, v246, v218
	v_fma_f32 v244, v128, v246, v242
	v_fma_f32 v245, v128, v247, v243
	v_cvt_pk_bf16_f32 v248, v244, v245
	ds_write_b32 v149, v248 offset:12960
	v_pk_add_f32 v[232:233], v[232:233], v[230:231]
	v_pk_add_f32 v[234:235], v[234:235], v[230:231]
	v_rcp_f32_e32 v232, v232
	v_fma_f32 v242, -v132, v245, v203
	v_fma_f32 v243, v132, v244, v219
	v_fma_f32 v246, v128, v244, v242
	v_fma_f32 v247, v128, v245, v243
	v_cvt_pk_bf16_f32 v249, v246, v247
	ds_write_b32 v149, v249 offset:13232
	v_rcp_f32_e32 v233, v233
	v_rcp_f32_e32 v234, v234
	v_rcp_f32_e32 v235, v235
	v_fma_f32 v242, -v132, v247, v204
	v_fma_f32 v243, v132, v246, v220
	v_fma_f32 v244, v128, v246, v242
	v_fma_f32 v245, v128, v247, v243
	v_cvt_pk_bf16_f32 v248, v244, v245
	ds_write_b32 v149, v248 offset:13504
	v_pk_mul_f32 v[232:233], v[72:73], v[232:233]
	v_pk_mul_f32 v[234:235], v[74:75], v[234:235]
	v_cvt_pk_bf16_f32 v236, v232, v232
	v_fma_f32 v242, -v132, v245, v205
	v_fma_f32 v243, v132, v244, v221
	v_fma_f32 v246, v128, v244, v242
	v_fma_f32 v247, v128, v245, v243
	v_cvt_pk_bf16_f32 v249, v246, v247
	ds_write_b32 v149, v249 offset:13776
	v_cvt_pk_bf16_f32 v237, v233, v233
	v_cvt_pk_bf16_f32 v238, v234, v234
	v_cvt_pk_bf16_f32 v239, v235, v235
	v_fma_f32 v242, -v132, v247, v206
	v_fma_f32 v243, v132, v246, v222
	v_fma_f32 v244, v128, v246, v242
	v_fma_f32 v245, v128, v247, v243
	v_cvt_pk_bf16_f32 v248, v244, v245
	ds_write_b32 v149, v248 offset:14048
	ds_write_b16 v160, v236 offset:15616
	ds_write_b16 v160, v237 offset:15648
	ds_write_b16 v160, v238 offset:15680
	v_fma_f32 v242, -v132, v245, v207
	v_fma_f32 v243, v132, v244, v223
	v_fma_f32 v86, v128, v244, v242
	v_fma_f32 v87, v128, v245, v243
	v_cvt_pk_bf16_f32 v249, v86, v87
	ds_write_b32 v149, v249 offset:14320
	ds_write_b16 v163, v239 offset:14592
	s_waitcnt lgkmcnt(0)
	ds_read_b128 v[72:75], v80 offset:10240
	ds_read_b128 v[76:79], v80 offset:10304
	ds_read_b128 v[184:187], v80 offset:10368
	ds_read_b128 v[188:191], v80 offset:10432
	s_waitcnt lgkmcnt(3)
	v_mfma_f32_16x16x32_bf16 v[68:71], v[72:75], v[32:35], v[68:71]
	s_waitcnt lgkmcnt(2)
	v_mfma_f32_16x16x32_bf16 v[68:71], v[76:79], v[36:39], v[68:71]
	s_waitcnt vmcnt(3)
	v_mov_b64_e32 v[82:83], v[54:55]
	v_mov_b64_e32 v[80:81], v[52:53]
	s_waitcnt lgkmcnt(1)
	v_mfma_f32_16x16x32_bf16 v[68:71], v[184:187], v[40:43], v[68:71]
	s_waitcnt lgkmcnt(0)
	v_mfma_f32_16x16x32_bf16 v[68:71], v[188:191], v[44:47], v[68:71]
	s_waitcnt vmcnt(2)
	v_mov_b64_e32 v[78:79], v[58:59]
	v_mov_b64_e32 v[76:77], v[56:57]
	s_nop 4
	v_pk_mul_f32 v[232:233], v[68:69], v[224:225]
	v_pk_mul_f32 v[234:235], v[70:71], v[224:225]
	v_pk_fma_f32 v[232:233], v[68:69], v[232:233], v[226:227]
	v_pk_fma_f32 v[234:235], v[70:71], v[234:235], v[226:227]
	v_pk_mul_f32 v[232:233], v[68:69], v[232:233]
	v_pk_mul_f32 v[234:235], v[70:71], v[234:235]
	v_pk_mul_f32 v[232:233], v[232:233], v[228:229]
	v_pk_mul_f32 v[234:235], v[234:235], v[228:229]
	v_exp_f32_e32 v232, v232
	v_exp_f32_e32 v233, v233
	v_exp_f32_e32 v234, v234
	v_exp_f32_e32 v235, v235
	v_pk_add_f32 v[232:233], v[232:233], v[230:231]
	v_pk_add_f32 v[234:235], v[234:235], v[230:231]
	v_rcp_f32_e32 v232, v232
	v_rcp_f32_e32 v233, v233
	v_rcp_f32_e32 v234, v234
	v_rcp_f32_e32 v235, v235
	v_pk_mul_f32 v[232:233], v[68:69], v[232:233]
	v_pk_mul_f32 v[234:235], v[70:71], v[234:235]
	v_cvt_pk_bf16_f32 v236, v232, v232
	v_cvt_pk_bf16_f32 v237, v233, v233
	v_cvt_pk_bf16_f32 v238, v234, v234
	v_cvt_pk_bf16_f32 v239, v235, v235
	ds_write_b16 v160, v236 offset:16128
	ds_write_b16 v160, v237 offset:16160
	ds_write_b16 v160, v238 offset:16192
	ds_write_b16 v164, v239 offset:14592
	s_waitcnt vmcnt(1)
	v_mov_b64_e32 v[74:75], v[62:63]
	v_mov_b64_e32 v[72:73], v[60:61]
	s_waitcnt lgkmcnt(0)
	s_waitcnt vmcnt(0)
	v_mov_b64_e32 v[70:71], v[66:67]
	v_mov_b64_e32 v[68:69], v[64:65]
